# scan token-shift: the LoRA-down wave packs two time steps per tanh pass (permlane32 swap), halving its serial work before the workgroup barrier
# speedup vs baseline: 1.1052x; 1.0115x over previous
; DI float bf2f(u16 v) { return __uint_as_float(((unsigned)v) << 16); }
;     ...
;     if (more) {
;       *(uint4*)(raw + (1 + (tid >> 5)) * 256 + vec * 8) = rg0;
;       *(uint4*)(raw + (9 + (tid >> 5)) * 256 + vec * 8) = rg1;
;       *(uint4*)(raw + (17 + (tid >> 5)) * 256 + vec * 8) = rg2;
;       *(uint4*)(raw + (25 + (tid >> 5)) * 256 + vec * 8) = rg3;
;       if (tid < 64) *(uint4*)(raw + ((tid >> 5) ? 33 : 0) * 256 + vec * 8) = rg4;
;       __syncthreads();
;       if (!(pm & 2)) {
;         float pv[34];
; #pragma unroll
;         for (int j = 0; j < 34; ++j) pv[j] = bf2f(raw[j * 256 + c]);
;         if (wv < 3) {
;           float* pdst = prep + (wv == 0 ? 256 + c : (wv == 1 ? 192 + (c - 64) : 320 + (c - 128)));
; #pragma unroll
;           for (int j = 0; j < 32; ++j) {
;             const float psv = pv[j + 1] + mu * (0.5f * (pv[j] + pv[j + 2]) - pv[j + 1]);
.LBB0_365:
	s_andn2_b64 vcc, exec, s[34:35]
	s_cbranch_vccnz .LBB0_350
	s_waitcnt vmcnt(3)
	ds_write_b128 v136, v[24:27] offset:49664
	s_waitcnt vmcnt(2)
	ds_write_b128 v136, v[28:31] offset:53760
	s_waitcnt vmcnt(1)
	ds_write_b128 v136, v[32:35] offset:57856
	s_waitcnt vmcnt(1)
	ds_write_b128 v136, v[36:39] offset:61952
	s_and_saveexec_b64 s[12:13], s[0:1]
	ds_write_b128 v137, v[40:43] offset:49152
	s_or_b64 exec, exec, s[12:13]
	s_waitcnt lgkmcnt(0)
	s_barrier
	ds_read_u16 v24, v138 offset:49152
	ds_read_u16 v25, v138 offset:49664
	ds_read_u16 v26, v138 offset:50176
	ds_read_u16 v27, v138 offset:50688
	ds_read_u16 v28, v138 offset:51200
	ds_read_u16 v29, v138 offset:51712
	ds_read_u16 v30, v138 offset:52224
	ds_read_u16 v31, v138 offset:52736
	ds_read_u16 v32, v138 offset:53248
	ds_read_u16 v33, v138 offset:53760
	ds_read_u16 v34, v138 offset:54272
	ds_read_u16 v35, v138 offset:54784
	ds_read_u16 v36, v138 offset:55296
	ds_read_u16 v37, v138 offset:55808
	ds_read_u16 v38, v138 offset:56320
	s_waitcnt lgkmcnt(14)
	v_lshlrev_b32_e32 v60, 16, v24
	ds_read_u16 v39, v138 offset:56832
	s_waitcnt lgkmcnt(14)
	v_lshlrev_b32_e32 v59, 16, v25
	ds_read_u16 v40, v138 offset:57344
	s_waitcnt lgkmcnt(14)
	v_lshlrev_b32_e32 v58, 16, v26
	ds_read_u16 v41, v138 offset:57856
	s_waitcnt lgkmcnt(14)
	v_lshlrev_b32_e32 v56, 16, v27
	ds_read_u16 v42, v138 offset:58368
	s_waitcnt lgkmcnt(14)
	v_lshlrev_b32_e32 v54, 16, v28
	ds_read_u16 v43, v138 offset:58880
	s_waitcnt lgkmcnt(14)
	v_lshlrev_b32_e32 v52, 16, v29
	ds_read_u16 v62, v138 offset:59392
	s_waitcnt lgkmcnt(14)
	v_lshlrev_b32_e32 v49, 16, v30
	ds_read_u16 v63, v138 offset:59904
	s_waitcnt lgkmcnt(14)
	v_lshlrev_b32_e32 v46, 16, v31
	ds_read_u16 v64, v138 offset:60416
	s_waitcnt lgkmcnt(14)
	v_lshlrev_b32_e32 v57, 16, v32
	ds_read_u16 v65, v138 offset:60928
	s_waitcnt lgkmcnt(14)
	v_lshlrev_b32_e32 v55, 16, v33
	ds_read_u16 v66, v138 offset:61440
	s_waitcnt lgkmcnt(14)
	v_lshlrev_b32_e32 v53, 16, v34
	ds_read_u16 v67, v138 offset:61952
	s_waitcnt lgkmcnt(14)
	v_lshlrev_b32_e32 v50, 16, v35
	ds_read_u16 v68, v138 offset:62464
	s_waitcnt lgkmcnt(14)
	v_lshlrev_b32_e32 v47, 16, v36
	ds_read_u16 v69, v138 offset:62976
	s_waitcnt lgkmcnt(14)
	v_lshlrev_b32_e32 v44, 16, v37
	ds_read_u16 v70, v138 offset:63488
	s_waitcnt lgkmcnt(14)
	v_lshlrev_b32_e32 v13, 16, v38
	ds_read_u16 v71, v138 offset:64000
	s_waitcnt lgkmcnt(14)
	v_lshlrev_b32_e32 v10, 16, v39
	ds_read_u16 v72, v138 offset:64512
	s_waitcnt lgkmcnt(14)
	v_lshlrev_b32_e32 v51, 16, v40
	ds_read_u16 v73, v138 offset:65024
	s_waitcnt lgkmcnt(14)
	v_lshlrev_b32_e32 v48, 16, v41
	ds_read_u16 v74, v139 offset:16384
	s_waitcnt lgkmcnt(14)
	v_lshlrev_b32_e32 v45, 16, v42
	ds_read_u16 v75, v139 offset:16896
	s_waitcnt lgkmcnt(14)
	v_lshlrev_b32_e32 v14, 16, v43
	s_waitcnt lgkmcnt(13)
	v_lshlrev_b32_e32 v11, 16, v62
	s_waitcnt lgkmcnt(12)
	v_lshlrev_b32_e32 v8, 16, v63
	s_waitcnt lgkmcnt(11)
	v_lshlrev_b32_e32 v6, 16, v64
	s_waitcnt lgkmcnt(10)
	v_lshlrev_b32_e32 v3, 16, v65
	s_waitcnt lgkmcnt(9)
	v_lshlrev_b32_e32 v15, 16, v66
	s_waitcnt lgkmcnt(8)
	v_lshlrev_b32_e32 v12, 16, v67
	s_waitcnt lgkmcnt(7)
	v_lshlrev_b32_e32 v9, 16, v68
	s_waitcnt lgkmcnt(6)
	v_lshlrev_b32_e32 v7, 16, v69
	s_waitcnt lgkmcnt(5)
	v_lshlrev_b32_e32 v4, 16, v70
	s_waitcnt lgkmcnt(4)
	v_lshlrev_b32_e32 v5, 16, v71
	s_waitcnt lgkmcnt(3)
	v_lshlrev_b32_e32 v2, 16, v72
	s_waitcnt lgkmcnt(2)
	v_lshlrev_b32_e32 v1, 16, v73
	s_waitcnt lgkmcnt(1)
	v_lshlrev_b32_e32 v0, 16, v74
	s_waitcnt lgkmcnt(0)
	v_lshlrev_b32_e32 v61, 16, v75
	v_add_f32_e32 v60, v60, v58
	v_add_f32_e32 v62, v59, v56
	v_add_f32_e32 v63, v58, v54
	v_add_f32_e32 v64, v56, v52
	v_add_f32_e32 v65, v54, v49
	v_add_f32_e32 v66, v52, v46
	v_add_f32_e32 v67, v49, v57
	v_add_f32_e32 v68, v46, v55
	v_add_f32_e32 v69, v57, v53
	v_add_f32_e32 v70, v55, v50
	v_add_f32_e32 v71, v53, v47
	v_add_f32_e32 v72, v50, v44
	v_add_f32_e32 v73, v47, v13
	v_add_f32_e32 v74, v44, v10
	v_add_f32_e32 v75, v13, v51
	v_add_f32_e32 v76, v10, v48
	v_add_f32_e32 v92, v51, v45
	v_add_f32_e32 v93, v48, v14
	v_add_f32_e32 v94, v45, v11
	v_add_f32_e32 v95, v14, v8
	v_add_f32_e32 v96, v11, v6
	v_add_f32_e32 v98, v8, v3
	v_add_f32_e32 v99, v6, v15
	v_add_f32_e32 v100, v3, v12
	v_add_f32_e32 v101, v15, v9
	v_add_f32_e32 v102, v12, v7
	v_add_f32_e32 v103, v9, v4
	v_add_f32_e32 v104, v7, v5
	v_add_f32_e32 v105, v4, v2
	v_add_f32_e32 v106, v5, v1
	v_add_f32_e32 v107, v2, v0
	v_add_f32_e32 v108, v1, v61
	s_mov_b64 s[12:13], -1
	s_andn2_b64 vcc, exec, s[88:89]
	v_fma_f32 v91, v60, 0.5, -v59
	v_fma_f32 v90, v62, 0.5, -v58
	v_fma_f32 v89, v63, 0.5, -v56
	v_fma_f32 v88, v64, 0.5, -v54
	v_fma_f32 v87, v65, 0.5, -v52
	v_fma_f32 v86, v66, 0.5, -v49
	v_fma_f32 v85, v67, 0.5, -v46
	v_fma_f32 v84, v68, 0.5, -v57
	v_fma_f32 v83, v69, 0.5, -v55
	v_fma_f32 v82, v70, 0.5, -v53
	v_fma_f32 v81, v71, 0.5, -v50
	v_fma_f32 v80, v72, 0.5, -v47
	v_fma_f32 v79, v73, 0.5, -v44
	v_fma_f32 v78, v74, 0.5, -v13
	v_fma_f32 v77, v75, 0.5, -v10
	v_fma_f32 v76, v76, 0.5, -v51
	v_fma_f32 v75, v92, 0.5, -v48
	v_fma_f32 v74, v93, 0.5, -v45
	v_fma_f32 v73, v94, 0.5, -v14
	v_fma_f32 v72, v95, 0.5, -v11
	v_fma_f32 v71, v96, 0.5, -v8
	v_fma_f32 v70, v98, 0.5, -v6
	v_fma_f32 v69, v99, 0.5, -v3
	v_fma_f32 v68, v100, 0.5, -v15
	v_fma_f32 v67, v101, 0.5, -v12
	v_fma_f32 v66, v102, 0.5, -v9
	v_fma_f32 v65, v103, 0.5, -v7
	v_fma_f32 v64, v104, 0.5, -v4
	v_fma_f32 v63, v105, 0.5, -v5
	v_fma_f32 v62, v106, 0.5, -v2
	v_fma_f32 v61, v107, 0.5, -v1
	v_fma_f32 v60, v108, 0.5, -v0
	s_cbranch_vccnz .LBB0_370
; DI u16 f2bf(float x) { unsigned u = __float_as_uint(x); u += 0x7fffu + ((u >> 16) & 1u); return (u16)(u >> 16); }
;     ...
;         } else {
;           u16* tdst = ((c < 224) ? twb : tab) + ((c - 192) & 31);
; #pragma unroll
;           for (int j = 0; j < 32; ++j) {
;             const float psv = pv[j + 1] + mu * (0.5f * (pv[j] + pv[j + 2]) - pv[j + 1]);
;             const float th = 1.f - 2.f * __builtin_amdgcn_rcpf(__expf(2.f * psv) + 1.f);
;             tdst[(dir ? 31 - j : j) * 40] = f2bf((c < 224) ? th : psv);
;           }
;         }
	s_sub_i32 s12, s97, s95
	v_and_b32_e32 v40, 31, v206
	v_lshlrev_b32_e32 v40, 1, v40
	v_add_u32_e32 v40, 0x10400, v40
	v_bfe_u32 v41, v206, 5, 1
	v_mul_lo_u32 v41, v41, s12
	v_add_u32_e32 v40, v40, v41
	v_add_u32_e32 v41, 0xa00, v40
	v_fma_f32 v24, v123, v91, v59
	v_fma_f32 v25, v123, v90, v58
	v_fma_f32 v28, v123, v89, v56
	v_fma_f32 v29, v123, v88, v54
	v_fma_f32 v32, v123, v87, v52
	v_fma_f32 v33, v123, v86, v49
	v_fma_f32 v36, v123, v85, v46
	v_fma_f32 v37, v123, v84, v57
	v_permlane32_swap_b32_e32 v24, v25
	v_permlane32_swap_b32_e32 v28, v29
	v_permlane32_swap_b32_e32 v32, v33
	v_permlane32_swap_b32_e32 v36, v37
	v_mul_f32_e32 v26, 0x4038aa3b, v24
	v_mul_f32_e32 v30, 0x4038aa3b, v28
	v_mul_f32_e32 v34, 0x4038aa3b, v32
	v_mul_f32_e32 v38, 0x4038aa3b, v36
	v_exp_f32_e32 v26, v26
	v_exp_f32_e32 v30, v30
	v_exp_f32_e32 v34, v34
	v_exp_f32_e32 v38, v38
	v_add_f32_e32 v26, 1.0, v26
	v_add_f32_e32 v30, 1.0, v30
	v_add_f32_e32 v34, 1.0, v34
	v_add_f32_e32 v38, 1.0, v38
	v_rcp_f32_e32 v26, v26
	v_rcp_f32_e32 v30, v30
	v_rcp_f32_e32 v34, v34
	v_rcp_f32_e32 v38, v38
	v_fma_f32 v24, v26, -2.0, 1.0
	v_fma_f32 v28, v30, -2.0, 1.0
	v_fma_f32 v32, v34, -2.0, 1.0
	v_fma_f32 v36, v38, -2.0, 1.0
	v_add_u32_e32 v26, s95, v40
	v_add_u32_e32 v30, s28, v40
	v_add_u32_e32 v34, s17, v40
	v_add_u32_e32 v38, s19, v40
	v_add_u32_e32 v27, s95, v41
	v_add_u32_e32 v31, s28, v41
	v_add_u32_e32 v35, s17, v41
	v_add_u32_e32 v39, s19, v41
	v_cvt_pk_bf16_f32 v24, v24, v25
	v_cvt_pk_bf16_f32 v28, v28, v29
	v_cvt_pk_bf16_f32 v32, v32, v33
	v_cvt_pk_bf16_f32 v36, v36, v37
	ds_write_b16 v26, v24
	ds_write_b16 v30, v28
	ds_write_b16 v34, v32
	ds_write_b16 v38, v36
	ds_write_b16_d16_hi v27, v24
	ds_write_b16_d16_hi v31, v28
	ds_write_b16_d16_hi v35, v32
	ds_write_b16_d16_hi v39, v36
	v_fma_f32 v24, v123, v83, v55
	v_fma_f32 v25, v123, v82, v53
	v_fma_f32 v28, v123, v81, v50
	v_fma_f32 v29, v123, v80, v47
	v_fma_f32 v32, v123, v79, v44
	v_fma_f32 v33, v123, v78, v13
	v_fma_f32 v36, v123, v77, v10
	v_fma_f32 v37, v123, v76, v51
	v_permlane32_swap_b32_e32 v24, v25
	v_permlane32_swap_b32_e32 v28, v29
	v_permlane32_swap_b32_e32 v32, v33
	v_permlane32_swap_b32_e32 v36, v37
	v_mul_f32_e32 v26, 0x4038aa3b, v24
	v_mul_f32_e32 v30, 0x4038aa3b, v28
	v_mul_f32_e32 v34, 0x4038aa3b, v32
	v_mul_f32_e32 v38, 0x4038aa3b, v36
	v_exp_f32_e32 v26, v26
	v_exp_f32_e32 v30, v30
	v_exp_f32_e32 v34, v34
	v_exp_f32_e32 v38, v38
	v_add_f32_e32 v26, 1.0, v26
	v_add_f32_e32 v30, 1.0, v30
	v_add_f32_e32 v34, 1.0, v34
	v_add_f32_e32 v38, 1.0, v38
	v_rcp_f32_e32 v26, v26
	v_rcp_f32_e32 v30, v30
	v_rcp_f32_e32 v34, v34
	v_rcp_f32_e32 v38, v38
	v_fma_f32 v24, v26, -2.0, 1.0
	v_fma_f32 v28, v30, -2.0, 1.0
	v_fma_f32 v32, v34, -2.0, 1.0
	v_fma_f32 v36, v38, -2.0, 1.0
	v_add_u32_e32 v26, s21, v40
	v_add_u32_e32 v30, s82, v40
	v_add_u32_e32 v34, s23, v40
	v_add_u32_e32 v38, s83, v40
	v_add_u32_e32 v27, s21, v41
	v_add_u32_e32 v31, s82, v41
	v_add_u32_e32 v35, s23, v41
	v_add_u32_e32 v39, s83, v41
	v_cvt_pk_bf16_f32 v24, v24, v25
	v_cvt_pk_bf16_f32 v28, v28, v29
	v_cvt_pk_bf16_f32 v32, v32, v33
	v_cvt_pk_bf16_f32 v36, v36, v37
	ds_write_b16 v26, v24
	ds_write_b16 v30, v28
	ds_write_b16 v34, v32
	ds_write_b16 v38, v36
	ds_write_b16_d16_hi v27, v24
	ds_write_b16_d16_hi v31, v28
	ds_write_b16_d16_hi v35, v32
	ds_write_b16_d16_hi v39, v36
	v_fma_f32 v24, v123, v75, v48
	v_fma_f32 v25, v123, v74, v45
	v_fma_f32 v28, v123, v73, v14
	v_fma_f32 v29, v123, v72, v11
	v_fma_f32 v32, v123, v71, v8
	v_fma_f32 v33, v123, v70, v6
	v_fma_f32 v36, v123, v69, v3
	v_fma_f32 v37, v123, v68, v15
	v_permlane32_swap_b32_e32 v24, v25
	v_permlane32_swap_b32_e32 v28, v29
	v_permlane32_swap_b32_e32 v32, v33
	v_permlane32_swap_b32_e32 v36, v37
	v_mul_f32_e32 v26, 0x4038aa3b, v24
	v_mul_f32_e32 v30, 0x4038aa3b, v28
	v_mul_f32_e32 v34, 0x4038aa3b, v32
	v_mul_f32_e32 v38, 0x4038aa3b, v36
	v_exp_f32_e32 v26, v26
	v_exp_f32_e32 v30, v30
	v_exp_f32_e32 v34, v34
	v_exp_f32_e32 v38, v38
	v_add_f32_e32 v26, 1.0, v26
	v_add_f32_e32 v30, 1.0, v30
	v_add_f32_e32 v34, 1.0, v34
	v_add_f32_e32 v38, 1.0, v38
	v_rcp_f32_e32 v26, v26
	v_rcp_f32_e32 v30, v30
	v_rcp_f32_e32 v34, v34
	v_rcp_f32_e32 v38, v38
	v_fma_f32 v24, v26, -2.0, 1.0
	v_fma_f32 v28, v30, -2.0, 1.0
	v_fma_f32 v32, v34, -2.0, 1.0
	v_fma_f32 v36, v38, -2.0, 1.0
	v_add_u32_e32 v26, s52, v40
	v_add_u32_e32 v30, s37, v40
	v_add_u32_e32 v34, s39, v40
	v_add_u32_e32 v38, s41, v40
	v_add_u32_e32 v27, s52, v41
	v_add_u32_e32 v31, s37, v41
	v_add_u32_e32 v35, s39, v41
	v_add_u32_e32 v39, s41, v41
	v_cvt_pk_bf16_f32 v24, v24, v25
	v_cvt_pk_bf16_f32 v28, v28, v29
	v_cvt_pk_bf16_f32 v32, v32, v33
	v_cvt_pk_bf16_f32 v36, v36, v37
	ds_write_b16 v26, v24
	ds_write_b16 v30, v28
	ds_write_b16 v34, v32
	ds_write_b16 v38, v36
	ds_write_b16_d16_hi v27, v24
	ds_write_b16_d16_hi v31, v28
	ds_write_b16_d16_hi v35, v32
	ds_write_b16_d16_hi v39, v36
	v_fma_f32 v24, v123, v67, v12
	v_fma_f32 v25, v123, v66, v9
	v_fma_f32 v28, v123, v65, v7
	v_fma_f32 v29, v123, v64, v4
	v_fma_f32 v32, v123, v63, v5
	v_fma_f32 v33, v123, v62, v2
	v_fma_f32 v36, v123, v61, v1
	v_fma_f32 v37, v123, v60, v0
	v_permlane32_swap_b32_e32 v24, v25
	v_permlane32_swap_b32_e32 v28, v29
	v_permlane32_swap_b32_e32 v32, v33
	v_permlane32_swap_b32_e32 v36, v37
	v_mul_f32_e32 v26, 0x4038aa3b, v24
	v_mul_f32_e32 v30, 0x4038aa3b, v28
	v_mul_f32_e32 v34, 0x4038aa3b, v32
	v_mul_f32_e32 v38, 0x4038aa3b, v36
	v_exp_f32_e32 v26, v26
	v_exp_f32_e32 v30, v30
	v_exp_f32_e32 v34, v34
	v_exp_f32_e32 v38, v38
	v_add_f32_e32 v26, 1.0, v26
	v_add_f32_e32 v30, 1.0, v30
	v_add_f32_e32 v34, 1.0, v34
	v_add_f32_e32 v38, 1.0, v38
	v_rcp_f32_e32 v26, v26
	v_rcp_f32_e32 v30, v30
	v_rcp_f32_e32 v34, v34
	v_rcp_f32_e32 v38, v38
	v_fma_f32 v24, v26, -2.0, 1.0
	v_fma_f32 v28, v30, -2.0, 1.0
	v_fma_f32 v32, v34, -2.0, 1.0
	v_fma_f32 v36, v38, -2.0, 1.0
	v_add_u32_e32 v26, s43, v40
	v_add_u32_e32 v30, s45, v40
	v_add_u32_e32 v34, s47, v40
	v_add_u32_e32 v38, s49, v40
	v_add_u32_e32 v27, s43, v41
	v_add_u32_e32 v31, s45, v41
	v_add_u32_e32 v35, s47, v41
	v_add_u32_e32 v39, s49, v41
	v_cvt_pk_bf16_f32 v24, v24, v25
	v_cvt_pk_bf16_f32 v28, v28, v29
	v_cvt_pk_bf16_f32 v32, v32, v33
	v_cvt_pk_bf16_f32 v36, v36, v37
	ds_write_b16 v26, v24
	ds_write_b16 v30, v28
	ds_write_b16 v34, v32
	ds_write_b16 v38, v36
	ds_write_b16_d16_hi v27, v24
	ds_write_b16_d16_hi v31, v28
	ds_write_b16_d16_hi v35, v32
	ds_write_b16_d16_hi v39, v36
	s_mov_b64 s[12:13], 0
